# v21 + GEMM loops: loop-bottom counter/pointer SALU moved in front of the final barrier (back-edge rotation)
# baseline (speedup 1.0000x reference)
.LBB0_239:
	s_add_u32 s10, s12, 0xfff80080
	s_addc_u32 s11, s13, -1
	s_add_i32 s64, 0, 0x10000
	s_cmp_eq_u32 s70, 28
	s_cselect_b32 s39, s25, s11
	s_cselect_b32 s38, s43, s10
	s_cselect_b32 s15, s23, s69
	s_cselect_b32 s14, s67, s68
	s_add_i32 s65, 0, 0x14000
	v_add_u32_e32 v152, s64, v160
	v_add_u32_e32 v156, s65, v160
	ds_read_b128 v[140:143], v152
	ds_read_b128 v[144:147], v152 offset:1024
	ds_read_b128 v[148:151], v152 offset:2048
	ds_read_b128 v[152:155], v152 offset:3072
	ds_read_b128 v[162:165], v156
	ds_read_b128 v[166:169], v156 offset:1024
	ds_read_b128 v[170:173], v156 offset:2048
	ds_read_b128 v[180:183], v156 offset:3072
	v_lshl_add_u64 v[156:157], s[12:13], 0, v[138:139]
	s_add_i32 m0, s40, 0xc000
	ds_read_b128 v[184:187], v161
	ds_read_b128 v[188:191], v161 offset:1024
	ds_read_b128 v[192:195], v161 offset:2048
	ds_read_b128 v[196:199], v161 offset:3072
	ds_read_b128 v[200:203], v161 offset:4096
	ds_read_b128 v[204:207], v161 offset:5120
	ds_read_b128 v[208:211], v161 offset:6144
	ds_read_b128 v[212:215], v161 offset:7168
	global_load_lds_dwordx4 v[156:157], off
	v_lshl_add_u64 v[156:157], s[12:13], 0, v[136:137]
	s_add_i32 m0, s40, 0xe000
	s_nop 0
	global_load_lds_dwordx4 v[156:157], off
	s_waitcnt vmcnt(8)
	s_waitcnt lgkmcnt(0)
	s_barrier
	s_setprio 1
	s_waitcnt lgkmcnt(0)
	v_mfma_f32_16x16x32_bf16 v[126:129], v[140:143], v[184:187], v[126:129]
	v_mfma_f32_16x16x32_bf16 v[122:125], v[148:151], v[184:187], v[122:125]
	v_mfma_f32_16x16x32_bf16 v[110:113], v[140:143], v[192:195], v[110:113]
	v_mfma_f32_16x16x32_bf16 v[106:109], v[148:151], v[192:195], v[106:109]
	v_mfma_f32_16x16x32_bf16 v[94:97], v[140:143], v[200:203], v[94:97]
	v_mfma_f32_16x16x32_bf16 v[90:93], v[148:151], v[200:203], v[90:93]
	v_mfma_f32_16x16x32_bf16 v[78:81], v[140:143], v[208:211], v[78:81]
	v_mfma_f32_16x16x32_bf16 v[74:77], v[148:151], v[208:211], v[74:77]
	v_mfma_f32_16x16x32_bf16 v[126:129], v[144:147], v[188:191], v[126:129]
	v_mfma_f32_16x16x32_bf16 v[122:125], v[152:155], v[188:191], v[122:125]
	v_mfma_f32_16x16x32_bf16 v[110:113], v[144:147], v[196:199], v[110:113]
	v_mfma_f32_16x16x32_bf16 v[106:109], v[152:155], v[196:199], v[106:109]
	v_mfma_f32_16x16x32_bf16 v[94:97], v[144:147], v[204:207], v[94:97]
	v_mfma_f32_16x16x32_bf16 v[90:93], v[152:155], v[204:207], v[90:93]
	v_mfma_f32_16x16x32_bf16 v[78:81], v[144:147], v[212:215], v[78:81]
	v_mfma_f32_16x16x32_bf16 v[74:77], v[152:155], v[212:215], v[74:77]
	s_setprio 0
	s_setprio 1
	v_mfma_f32_16x16x32_bf16 v[118:121], v[162:165], v[184:187], v[118:121]
	v_mfma_f32_16x16x32_bf16 v[114:117], v[170:173], v[184:187], v[114:117]
	v_mfma_f32_16x16x32_bf16 v[102:105], v[162:165], v[192:195], v[102:105]
	v_mfma_f32_16x16x32_bf16 v[98:101], v[170:173], v[192:195], v[98:101]
	v_mfma_f32_16x16x32_bf16 v[86:89], v[162:165], v[200:203], v[86:89]
	v_mfma_f32_16x16x32_bf16 v[82:85], v[170:173], v[200:203], v[82:85]
	v_mfma_f32_16x16x32_bf16 v[70:73], v[162:165], v[208:211], v[70:73]
	v_mfma_f32_16x16x32_bf16 v[66:69], v[170:173], v[208:211], v[66:69]
	v_mfma_f32_16x16x32_bf16 v[118:121], v[166:169], v[188:191], v[118:121]
	v_mfma_f32_16x16x32_bf16 v[114:117], v[180:183], v[188:191], v[114:117]
	v_mfma_f32_16x16x32_bf16 v[102:105], v[166:169], v[196:199], v[102:105]
	v_mfma_f32_16x16x32_bf16 v[98:101], v[180:183], v[196:199], v[98:101]
	v_mfma_f32_16x16x32_bf16 v[86:89], v[166:169], v[204:207], v[86:89]
	v_mfma_f32_16x16x32_bf16 v[82:85], v[180:183], v[204:207], v[82:85]
	v_mfma_f32_16x16x32_bf16 v[70:73], v[166:169], v[212:215], v[70:73]
	v_mfma_f32_16x16x32_bf16 v[66:69], v[180:183], v[212:215], v[66:69]
	s_setprio 2
	s_barrier
	s_add_i32 s10, s64, s37
	v_lshl_add_u64 v[156:157], s[14:15], 0, v[0:1]
	s_mov_b32 m0, s10
	ds_read_b128 v[184:187], v161 offset:16384
	ds_read_b128 v[188:191], v161 offset:17408
	ds_read_b128 v[192:195], v161 offset:18432
	ds_read_b128 v[196:199], v161 offset:19456
	ds_read_b128 v[200:203], v161 offset:20480
	ds_read_b128 v[204:207], v161 offset:21504
	ds_read_b128 v[208:211], v161 offset:22528
	ds_read_b128 v[212:215], v161 offset:23552
	global_load_lds_dwordx4 v[156:157], off
	s_add_i32 m0, s10, 0x2000
	s_add_u32 s10, s14, 0x80000
	v_lshl_add_u64 v[174:175], s[14:15], 0, v[130:131]
	s_addc_u32 s11, s15, 0
	s_add_i32 s64, s65, s37
	global_load_lds_dwordx4 v[174:175], off
	v_lshl_add_u64 v[176:177], s[10:11], 0, v[0:1]
	s_mov_b32 m0, s64
	v_lshl_add_u64 v[178:179], s[38:39], 0, v[132:133]
	global_load_lds_dwordx4 v[176:177], off
	v_lshl_add_u64 v[176:177], s[10:11], 0, v[130:131]
	s_add_i32 m0, s64, 0x2000
	s_nop 0
	global_load_lds_dwordx4 v[176:177], off
	v_lshl_add_u64 v[176:177], s[38:39], 0, v[134:135]
	s_mov_b32 m0, s40
	s_nop 0
	global_load_lds_dwordx4 v[176:177], off
	s_mov_b32 m0, s41
	s_nop 0
	global_load_lds_dwordx4 v[178:179], off
	s_waitcnt vmcnt(8)
	s_waitcnt lgkmcnt(0)
	s_barrier
	s_setprio 1
	s_waitcnt lgkmcnt(0)
	v_mfma_f32_16x16x32_bf16 v[62:65], v[140:143], v[184:187], v[62:65]
	v_mfma_f32_16x16x32_bf16 v[58:61], v[148:151], v[184:187], v[58:61]
	v_mfma_f32_16x16x32_bf16 v[46:49], v[140:143], v[192:195], v[46:49]
	v_mfma_f32_16x16x32_bf16 v[42:45], v[148:151], v[192:195], v[42:45]
	v_mfma_f32_16x16x32_bf16 v[30:33], v[140:143], v[200:203], v[30:33]
	v_mfma_f32_16x16x32_bf16 v[26:29], v[148:151], v[200:203], v[26:29]
	v_mfma_f32_16x16x32_bf16 v[14:17], v[140:143], v[208:211], v[14:17]
	v_mfma_f32_16x16x32_bf16 v[10:13], v[148:151], v[208:211], v[10:13]
	v_mfma_f32_16x16x32_bf16 v[62:65], v[144:147], v[188:191], v[62:65]
	v_mfma_f32_16x16x32_bf16 v[58:61], v[152:155], v[188:191], v[58:61]
	v_mfma_f32_16x16x32_bf16 v[46:49], v[144:147], v[196:199], v[46:49]
	v_mfma_f32_16x16x32_bf16 v[42:45], v[152:155], v[196:199], v[42:45]
	v_mfma_f32_16x16x32_bf16 v[30:33], v[144:147], v[204:207], v[30:33]
	v_mfma_f32_16x16x32_bf16 v[26:29], v[152:155], v[204:207], v[26:29]
	v_mfma_f32_16x16x32_bf16 v[14:17], v[144:147], v[212:215], v[14:17]
	v_mfma_f32_16x16x32_bf16 v[10:13], v[152:155], v[212:215], v[10:13]
	s_setprio 0
	s_setprio 1
	v_mfma_f32_16x16x32_bf16 v[54:57], v[162:165], v[184:187], v[54:57]
	v_mfma_f32_16x16x32_bf16 v[50:53], v[170:173], v[184:187], v[50:53]
	v_mfma_f32_16x16x32_bf16 v[38:41], v[162:165], v[192:195], v[38:41]
	v_mfma_f32_16x16x32_bf16 v[34:37], v[170:173], v[192:195], v[34:37]
	v_mfma_f32_16x16x32_bf16 v[22:25], v[162:165], v[200:203], v[22:25]
	v_mfma_f32_16x16x32_bf16 v[18:21], v[170:173], v[200:203], v[18:21]
	v_mfma_f32_16x16x32_bf16 v[6:9], v[162:165], v[208:211], v[6:9]
	v_mfma_f32_16x16x32_bf16 v[2:5], v[170:173], v[208:211], v[2:5]
	v_mfma_f32_16x16x32_bf16 v[54:57], v[166:169], v[188:191], v[54:57]
	v_mfma_f32_16x16x32_bf16 v[50:53], v[180:183], v[188:191], v[50:53]
	v_mfma_f32_16x16x32_bf16 v[38:41], v[166:169], v[196:199], v[38:41]
	v_mfma_f32_16x16x32_bf16 v[34:37], v[180:183], v[196:199], v[34:37]
	v_mfma_f32_16x16x32_bf16 v[22:25], v[166:169], v[204:207], v[22:25]
	v_mfma_f32_16x16x32_bf16 v[18:21], v[180:183], v[204:207], v[18:21]
	v_mfma_f32_16x16x32_bf16 v[6:9], v[166:169], v[212:215], v[6:9]
	v_mfma_f32_16x16x32_bf16 v[2:5], v[180:183], v[212:215], v[2:5]
	s_setprio 2
	s_barrier
	s_add_i32 s64, 0, 0x18000
	s_add_i32 s65, 0, 0x1c000
	v_add_u32_e32 v152, s64, v160
	v_add_u32_e32 v180, s65, v160
	ds_read_b128 v[140:143], v152
	ds_read_b128 v[144:147], v152 offset:1024
	ds_read_b128 v[148:151], v152 offset:2048
	ds_read_b128 v[152:155], v152 offset:3072
	ds_read_b128 v[162:165], v180
	ds_read_b128 v[166:169], v180 offset:1024
	ds_read_b128 v[170:173], v180 offset:2048
	ds_read_b128 v[180:183], v180 offset:3072
	s_add_u32 s10, s38, 0x80000
	s_addc_u32 s11, s39, 0
	s_mov_b32 m0, s44
	v_lshl_add_u64 v[216:217], s[10:11], 0, v[134:135]
	ds_read_b128 v[184:187], v161 offset:32768
	ds_read_b128 v[188:191], v161 offset:33792
	ds_read_b128 v[192:195], v161 offset:34816
	ds_read_b128 v[196:199], v161 offset:35840
	ds_read_b128 v[200:203], v161 offset:36864
	ds_read_b128 v[204:207], v161 offset:37888
	ds_read_b128 v[208:211], v161 offset:38912
	ds_read_b128 v[212:215], v161 offset:39936
	global_load_lds_dwordx4 v[216:217], off
	v_lshl_add_u64 v[216:217], s[10:11], 0, v[132:133]
	s_mov_b32 m0, s45
	s_nop 0
	global_load_lds_dwordx4 v[216:217], off
	s_waitcnt vmcnt(8)
	s_waitcnt lgkmcnt(0)
	s_barrier
	s_setprio 1
	s_waitcnt lgkmcnt(0)
	v_mfma_f32_16x16x32_bf16 v[126:129], v[140:143], v[184:187], v[126:129]
	v_mfma_f32_16x16x32_bf16 v[122:125], v[148:151], v[184:187], v[122:125]
	v_mfma_f32_16x16x32_bf16 v[110:113], v[140:143], v[192:195], v[110:113]
	v_mfma_f32_16x16x32_bf16 v[106:109], v[148:151], v[192:195], v[106:109]
	v_mfma_f32_16x16x32_bf16 v[94:97], v[140:143], v[200:203], v[94:97]
	v_mfma_f32_16x16x32_bf16 v[90:93], v[148:151], v[200:203], v[90:93]
	v_mfma_f32_16x16x32_bf16 v[78:81], v[140:143], v[208:211], v[78:81]
	v_mfma_f32_16x16x32_bf16 v[74:77], v[148:151], v[208:211], v[74:77]
	v_mfma_f32_16x16x32_bf16 v[126:129], v[144:147], v[188:191], v[126:129]
	v_mfma_f32_16x16x32_bf16 v[122:125], v[152:155], v[188:191], v[122:125]
	v_mfma_f32_16x16x32_bf16 v[110:113], v[144:147], v[196:199], v[110:113]
	v_mfma_f32_16x16x32_bf16 v[106:109], v[152:155], v[196:199], v[106:109]
	v_mfma_f32_16x16x32_bf16 v[94:97], v[144:147], v[204:207], v[94:97]
	v_mfma_f32_16x16x32_bf16 v[90:93], v[152:155], v[204:207], v[90:93]
	v_mfma_f32_16x16x32_bf16 v[78:81], v[144:147], v[212:215], v[78:81]
	v_mfma_f32_16x16x32_bf16 v[74:77], v[152:155], v[212:215], v[74:77]
	s_setprio 0
	s_setprio 1
	v_mfma_f32_16x16x32_bf16 v[118:121], v[162:165], v[184:187], v[118:121]
	v_mfma_f32_16x16x32_bf16 v[114:117], v[170:173], v[184:187], v[114:117]
	v_mfma_f32_16x16x32_bf16 v[102:105], v[162:165], v[192:195], v[102:105]
	v_mfma_f32_16x16x32_bf16 v[98:101], v[170:173], v[192:195], v[98:101]
	v_mfma_f32_16x16x32_bf16 v[86:89], v[162:165], v[200:203], v[86:89]
	v_mfma_f32_16x16x32_bf16 v[82:85], v[170:173], v[200:203], v[82:85]
	v_mfma_f32_16x16x32_bf16 v[70:73], v[162:165], v[208:211], v[70:73]
	v_mfma_f32_16x16x32_bf16 v[66:69], v[170:173], v[208:211], v[66:69]
	v_mfma_f32_16x16x32_bf16 v[118:121], v[166:169], v[188:191], v[118:121]
	v_mfma_f32_16x16x32_bf16 v[114:117], v[180:183], v[188:191], v[114:117]
	v_mfma_f32_16x16x32_bf16 v[102:105], v[166:169], v[196:199], v[102:105]
	v_mfma_f32_16x16x32_bf16 v[98:101], v[180:183], v[196:199], v[98:101]
	v_mfma_f32_16x16x32_bf16 v[86:89], v[166:169], v[204:207], v[86:89]
	v_mfma_f32_16x16x32_bf16 v[82:85], v[180:183], v[204:207], v[82:85]
	v_mfma_f32_16x16x32_bf16 v[70:73], v[166:169], v[212:215], v[70:73]
	v_mfma_f32_16x16x32_bf16 v[66:69], v[180:183], v[212:215], v[66:69]
	s_setprio 2
	s_barrier
	s_add_i32 s10, s64, s37
	v_lshl_add_u64 v[156:157], v[156:157], 0, s[94:95]
	s_mov_b32 m0, s10
	ds_read_b128 v[184:187], v161 offset:49152
	ds_read_b128 v[188:191], v161 offset:50176
	ds_read_b128 v[192:195], v161 offset:51200
	ds_read_b128 v[196:199], v161 offset:52224
	ds_read_b128 v[200:203], v161 offset:53248
	ds_read_b128 v[204:207], v161 offset:54272
	ds_read_b128 v[208:211], v161 offset:55296
	ds_read_b128 v[212:215], v161 offset:56320
	global_load_lds_dwordx4 v[156:157], off
	s_add_i32 m0, s10, 0x2000
	s_add_u32 s10, s14, 0x80080
	v_lshl_add_u64 v[156:157], v[174:175], 0, s[94:95]
	s_addc_u32 s11, s15, 0
	s_add_i32 s14, s65, s37
	global_load_lds_dwordx4 v[156:157], off
	v_lshl_add_u64 v[156:157], s[10:11], 0, v[0:1]
	s_mov_b32 m0, s14
	s_nop 0
	global_load_lds_dwordx4 v[156:157], off
	v_lshl_add_u64 v[156:157], s[10:11], 0, v[130:131]
	s_add_i32 m0, s14, 0x2000
	s_nop 0
	global_load_lds_dwordx4 v[156:157], off
	v_lshl_add_u64 v[156:157], v[176:177], 0, s[94:95]
	s_mov_b32 m0, s60
	s_nop 0
	global_load_lds_dwordx4 v[156:157], off
	v_lshl_add_u64 v[156:157], v[178:179], 0, s[94:95]
	s_mov_b32 m0, s61
	s_nop 0
	global_load_lds_dwordx4 v[156:157], off
	s_waitcnt vmcnt(8)
	s_waitcnt lgkmcnt(0)
	s_barrier
	s_setprio 1
	s_waitcnt lgkmcnt(0)
	v_mfma_f32_16x16x32_bf16 v[62:65], v[140:143], v[184:187], v[62:65]
	v_mfma_f32_16x16x32_bf16 v[58:61], v[148:151], v[184:187], v[58:61]
	v_mfma_f32_16x16x32_bf16 v[46:49], v[140:143], v[192:195], v[46:49]
	v_mfma_f32_16x16x32_bf16 v[42:45], v[148:151], v[192:195], v[42:45]
	v_mfma_f32_16x16x32_bf16 v[30:33], v[140:143], v[200:203], v[30:33]
	v_mfma_f32_16x16x32_bf16 v[26:29], v[148:151], v[200:203], v[26:29]
	v_mfma_f32_16x16x32_bf16 v[14:17], v[140:143], v[208:211], v[14:17]
	v_mfma_f32_16x16x32_bf16 v[10:13], v[148:151], v[208:211], v[10:13]
	v_mfma_f32_16x16x32_bf16 v[62:65], v[144:147], v[188:191], v[62:65]
	v_mfma_f32_16x16x32_bf16 v[58:61], v[152:155], v[188:191], v[58:61]
	v_mfma_f32_16x16x32_bf16 v[46:49], v[144:147], v[196:199], v[46:49]
	v_mfma_f32_16x16x32_bf16 v[42:45], v[152:155], v[196:199], v[42:45]
	v_mfma_f32_16x16x32_bf16 v[30:33], v[144:147], v[204:207], v[30:33]
	v_mfma_f32_16x16x32_bf16 v[26:29], v[152:155], v[204:207], v[26:29]
	v_mfma_f32_16x16x32_bf16 v[14:17], v[144:147], v[212:215], v[14:17]
	v_mfma_f32_16x16x32_bf16 v[10:13], v[152:155], v[212:215], v[10:13]
	s_setprio 0
	s_setprio 1
	v_mfma_f32_16x16x32_bf16 v[54:57], v[162:165], v[184:187], v[54:57]
	v_mfma_f32_16x16x32_bf16 v[50:53], v[170:173], v[184:187], v[50:53]
	v_mfma_f32_16x16x32_bf16 v[38:41], v[162:165], v[192:195], v[38:41]
	v_mfma_f32_16x16x32_bf16 v[34:37], v[170:173], v[192:195], v[34:37]
	v_mfma_f32_16x16x32_bf16 v[22:25], v[162:165], v[200:203], v[22:25]
	v_mfma_f32_16x16x32_bf16 v[18:21], v[170:173], v[200:203], v[18:21]
	v_mfma_f32_16x16x32_bf16 v[6:9], v[162:165], v[208:211], v[6:9]
	v_mfma_f32_16x16x32_bf16 v[2:5], v[170:173], v[208:211], v[2:5]
	v_mfma_f32_16x16x32_bf16 v[54:57], v[166:169], v[188:191], v[54:57]
	v_mfma_f32_16x16x32_bf16 v[50:53], v[180:183], v[188:191], v[50:53]
	v_mfma_f32_16x16x32_bf16 v[38:41], v[166:169], v[196:199], v[38:41]
	v_mfma_f32_16x16x32_bf16 v[34:37], v[180:183], v[196:199], v[34:37]
	v_mfma_f32_16x16x32_bf16 v[22:25], v[166:169], v[204:207], v[22:25]
	v_mfma_f32_16x16x32_bf16 v[18:21], v[180:183], v[204:207], v[18:21]
	v_mfma_f32_16x16x32_bf16 v[6:9], v[166:169], v[212:215], v[6:9]
	v_mfma_f32_16x16x32_bf16 v[2:5], v[180:183], v[212:215], v[2:5]
	s_setprio 2
	s_add_i32 s70, s70, 2
	s_add_u32 s68, s68, 0x100
	s_addc_u32 s69, s69, 0
	s_add_u32 s12, s12, 0x100
	s_addc_u32 s13, s13, 0
	s_cmp_gt_u32 s70, 29
	s_barrier
	s_cbranch_scc0 .LBB0_239
	s_and_b64 vcc, exec, s[20:21]
	s_cbranch_vccz .LBB0_242
	s_barrier

.LBB0_341:
	s_add_u32 s10, s12, 0xfff00080
	s_addc_u32 s11, s13, -1
	s_add_i32 s64, 0, 0x10000
	s_cmp_eq_u32 s72, 4
	s_cselect_b32 s45, s25, s11
	s_cselect_b32 s44, s68, s10
	s_cselect_b32 s43, s23, s71
	s_cselect_b32 s42, s69, s70
	s_add_i32 s65, 0, 0x14000
	v_add_u32_e32 v152, s64, v162
	v_add_u32_e32 v172, s65, v162
	ds_read_b128 v[140:143], v152
	ds_read_b128 v[144:147], v152 offset:1024
	ds_read_b128 v[148:151], v152 offset:2048
	ds_read_b128 v[152:155], v152 offset:3072
	ds_read_b128 v[156:159], v172
	ds_read_b128 v[164:167], v172 offset:1024
	ds_read_b128 v[168:171], v172 offset:2048
	ds_read_b128 v[172:175], v172 offset:3072
	v_lshl_add_u64 v[176:177], s[12:13], 0, v[138:139]
	s_add_i32 m0, s33, 0xc000
	ds_read_b128 v[180:183], v163
	ds_read_b128 v[184:187], v163 offset:1024
	ds_read_b128 v[188:191], v163 offset:2048
	ds_read_b128 v[192:195], v163 offset:3072
	ds_read_b128 v[196:199], v163 offset:4096
	ds_read_b128 v[200:203], v163 offset:5120
	ds_read_b128 v[204:207], v163 offset:6144
	ds_read_b128 v[208:211], v163 offset:7168
	global_load_lds_dwordx4 v[176:177], off
	v_lshl_add_u64 v[176:177], s[12:13], 0, v[136:137]
	s_add_i32 m0, s33, 0xe000
	s_nop 0
	global_load_lds_dwordx4 v[176:177], off
	s_waitcnt vmcnt(8)
	s_waitcnt lgkmcnt(0)
	s_barrier
	s_setprio 1
	s_waitcnt lgkmcnt(0)
	v_mfma_f32_16x16x32_bf16 v[126:129], v[140:143], v[180:183], v[126:129]
	v_mfma_f32_16x16x32_bf16 v[122:125], v[148:151], v[180:183], v[122:125]
	v_mfma_f32_16x16x32_bf16 v[118:121], v[140:143], v[188:191], v[118:121]
	v_mfma_f32_16x16x32_bf16 v[114:117], v[148:151], v[188:191], v[114:117]
	v_mfma_f32_16x16x32_bf16 v[94:97], v[140:143], v[196:199], v[94:97]
	v_mfma_f32_16x16x32_bf16 v[90:93], v[148:151], v[196:199], v[90:93]
	v_mfma_f32_16x16x32_bf16 v[78:81], v[140:143], v[204:207], v[78:81]
	v_mfma_f32_16x16x32_bf16 v[74:77], v[148:151], v[204:207], v[74:77]
	v_mfma_f32_16x16x32_bf16 v[126:129], v[144:147], v[184:187], v[126:129]
	v_mfma_f32_16x16x32_bf16 v[122:125], v[152:155], v[184:187], v[122:125]
	v_mfma_f32_16x16x32_bf16 v[118:121], v[144:147], v[192:195], v[118:121]
	v_mfma_f32_16x16x32_bf16 v[114:117], v[152:155], v[192:195], v[114:117]
	v_mfma_f32_16x16x32_bf16 v[94:97], v[144:147], v[200:203], v[94:97]
	v_mfma_f32_16x16x32_bf16 v[90:93], v[152:155], v[200:203], v[90:93]
	v_mfma_f32_16x16x32_bf16 v[78:81], v[144:147], v[208:211], v[78:81]
	v_mfma_f32_16x16x32_bf16 v[74:77], v[152:155], v[208:211], v[74:77]
	s_setprio 0
	s_setprio 1
	v_mfma_f32_16x16x32_bf16 v[110:113], v[156:159], v[180:183], v[110:113]
	v_mfma_f32_16x16x32_bf16 v[106:109], v[168:171], v[180:183], v[106:109]
	v_mfma_f32_16x16x32_bf16 v[102:105], v[156:159], v[188:191], v[102:105]
	v_mfma_f32_16x16x32_bf16 v[98:101], v[168:171], v[188:191], v[98:101]
	v_mfma_f32_16x16x32_bf16 v[86:89], v[156:159], v[196:199], v[86:89]
	v_mfma_f32_16x16x32_bf16 v[82:85], v[168:171], v[196:199], v[82:85]
	v_mfma_f32_16x16x32_bf16 v[70:73], v[156:159], v[204:207], v[70:73]
	v_mfma_f32_16x16x32_bf16 v[66:69], v[168:171], v[204:207], v[66:69]
	v_mfma_f32_16x16x32_bf16 v[110:113], v[164:167], v[184:187], v[110:113]
	v_mfma_f32_16x16x32_bf16 v[106:109], v[172:175], v[184:187], v[106:109]
	v_mfma_f32_16x16x32_bf16 v[102:105], v[164:167], v[192:195], v[102:105]
	v_mfma_f32_16x16x32_bf16 v[98:101], v[172:175], v[192:195], v[98:101]
	v_mfma_f32_16x16x32_bf16 v[86:89], v[164:167], v[200:203], v[86:89]
	v_mfma_f32_16x16x32_bf16 v[82:85], v[172:175], v[200:203], v[82:85]
	v_mfma_f32_16x16x32_bf16 v[70:73], v[164:167], v[208:211], v[70:73]
	v_mfma_f32_16x16x32_bf16 v[66:69], v[172:175], v[208:211], v[66:69]
	s_setprio 2
	s_barrier
	s_add_i32 s10, s64, s28
	v_lshl_add_u64 v[176:177], s[42:43], 0, v[0:1]
	s_mov_b32 m0, s10
	ds_read_b128 v[180:183], v163 offset:16384
	ds_read_b128 v[184:187], v163 offset:17408
	ds_read_b128 v[188:191], v163 offset:18432
	ds_read_b128 v[192:195], v163 offset:19456
	ds_read_b128 v[196:199], v163 offset:20480
	ds_read_b128 v[200:203], v163 offset:21504
	ds_read_b128 v[204:207], v163 offset:22528
	ds_read_b128 v[208:211], v163 offset:23552
	global_load_lds_dwordx4 v[176:177], off
	s_add_i32 m0, s10, 0x2000
	s_add_u32 s10, s42, 0x20000
	v_lshl_add_u64 v[178:179], s[42:43], 0, v[130:131]
	s_addc_u32 s11, s43, 0
	s_add_i32 s64, s65, s28
	global_load_lds_dwordx4 v[178:179], off
	v_lshl_add_u64 v[212:213], s[10:11], 0, v[0:1]
	s_mov_b32 m0, s64
	v_lshl_add_u64 v[214:215], s[44:45], 0, v[132:133]
	global_load_lds_dwordx4 v[212:213], off
	v_lshl_add_u64 v[212:213], s[10:11], 0, v[130:131]
	s_add_i32 m0, s64, 0x2000
	s_nop 0
	global_load_lds_dwordx4 v[212:213], off
	v_lshl_add_u64 v[212:213], s[44:45], 0, v[134:135]
	s_mov_b32 m0, s33
	s_nop 0
	global_load_lds_dwordx4 v[212:213], off
	s_mov_b32 m0, s37
	s_nop 0
	global_load_lds_dwordx4 v[214:215], off
	s_waitcnt vmcnt(8)
	s_waitcnt lgkmcnt(0)
	s_barrier
	s_setprio 1
	s_waitcnt lgkmcnt(0)
	v_mfma_f32_16x16x32_bf16 v[62:65], v[140:143], v[180:183], v[62:65]
	v_mfma_f32_16x16x32_bf16 v[58:61], v[148:151], v[180:183], v[58:61]
	v_mfma_f32_16x16x32_bf16 v[46:49], v[140:143], v[188:191], v[46:49]
	v_mfma_f32_16x16x32_bf16 v[42:45], v[148:151], v[188:191], v[42:45]
	v_mfma_f32_16x16x32_bf16 v[30:33], v[140:143], v[196:199], v[30:33]
	v_mfma_f32_16x16x32_bf16 v[26:29], v[148:151], v[196:199], v[26:29]
	v_mfma_f32_16x16x32_bf16 v[14:17], v[140:143], v[204:207], v[14:17]
	v_mfma_f32_16x16x32_bf16 v[10:13], v[148:151], v[204:207], v[10:13]
	v_mfma_f32_16x16x32_bf16 v[62:65], v[144:147], v[184:187], v[62:65]
	v_mfma_f32_16x16x32_bf16 v[58:61], v[152:155], v[184:187], v[58:61]
	v_mfma_f32_16x16x32_bf16 v[46:49], v[144:147], v[192:195], v[46:49]
	v_mfma_f32_16x16x32_bf16 v[42:45], v[152:155], v[192:195], v[42:45]
	v_mfma_f32_16x16x32_bf16 v[30:33], v[144:147], v[200:203], v[30:33]
	v_mfma_f32_16x16x32_bf16 v[26:29], v[152:155], v[200:203], v[26:29]
	v_mfma_f32_16x16x32_bf16 v[14:17], v[144:147], v[208:211], v[14:17]
	v_mfma_f32_16x16x32_bf16 v[10:13], v[152:155], v[208:211], v[10:13]
	s_setprio 0
	s_setprio 1
	v_mfma_f32_16x16x32_bf16 v[54:57], v[156:159], v[180:183], v[54:57]
	v_mfma_f32_16x16x32_bf16 v[50:53], v[168:171], v[180:183], v[50:53]
	v_mfma_f32_16x16x32_bf16 v[38:41], v[156:159], v[188:191], v[38:41]
	v_mfma_f32_16x16x32_bf16 v[34:37], v[168:171], v[188:191], v[34:37]
	v_mfma_f32_16x16x32_bf16 v[22:25], v[156:159], v[196:199], v[22:25]
	v_mfma_f32_16x16x32_bf16 v[18:21], v[168:171], v[196:199], v[18:21]
	v_mfma_f32_16x16x32_bf16 v[6:9], v[156:159], v[204:207], v[6:9]
	v_mfma_f32_16x16x32_bf16 v[2:5], v[168:171], v[204:207], v[2:5]
	v_mfma_f32_16x16x32_bf16 v[54:57], v[164:167], v[184:187], v[54:57]
	v_mfma_f32_16x16x32_bf16 v[50:53], v[172:175], v[184:187], v[50:53]
	v_mfma_f32_16x16x32_bf16 v[38:41], v[164:167], v[192:195], v[38:41]
	v_mfma_f32_16x16x32_bf16 v[34:37], v[172:175], v[192:195], v[34:37]
	v_mfma_f32_16x16x32_bf16 v[22:25], v[164:167], v[200:203], v[22:25]
	v_mfma_f32_16x16x32_bf16 v[18:21], v[172:175], v[200:203], v[18:21]
	v_mfma_f32_16x16x32_bf16 v[6:9], v[164:167], v[208:211], v[6:9]
	v_mfma_f32_16x16x32_bf16 v[2:5], v[172:175], v[208:211], v[2:5]
	s_setprio 2
	s_barrier
	s_add_i32 s64, 0, 0x18000
	s_add_i32 s65, 0, 0x1c000
	v_add_u32_e32 v152, s64, v162
	v_add_u32_e32 v172, s65, v162
	ds_read_b128 v[140:143], v152
	ds_read_b128 v[144:147], v152 offset:1024
	ds_read_b128 v[148:151], v152 offset:2048
	ds_read_b128 v[152:155], v152 offset:3072
	ds_read_b128 v[156:159], v172
	ds_read_b128 v[164:167], v172 offset:1024
	ds_read_b128 v[168:171], v172 offset:2048
	ds_read_b128 v[172:175], v172 offset:3072
	s_add_u32 s10, s44, 0x100000
	s_addc_u32 s11, s45, 0
	s_mov_b32 m0, s40
	v_lshl_add_u64 v[216:217], s[10:11], 0, v[134:135]
	ds_read_b128 v[180:183], v163 offset:32768
	ds_read_b128 v[184:187], v163 offset:33792
	ds_read_b128 v[188:191], v163 offset:34816
	ds_read_b128 v[192:195], v163 offset:35840
	ds_read_b128 v[196:199], v163 offset:36864
	ds_read_b128 v[200:203], v163 offset:37888
	ds_read_b128 v[204:207], v163 offset:38912
	ds_read_b128 v[208:211], v163 offset:39936
	global_load_lds_dwordx4 v[216:217], off
	v_lshl_add_u64 v[216:217], s[10:11], 0, v[132:133]
	s_mov_b32 m0, s41
	s_nop 0
	global_load_lds_dwordx4 v[216:217], off
	s_waitcnt vmcnt(8)
	s_waitcnt lgkmcnt(0)
	s_barrier
	s_setprio 1
	s_waitcnt lgkmcnt(0)
	v_mfma_f32_16x16x32_bf16 v[126:129], v[140:143], v[180:183], v[126:129]
	v_mfma_f32_16x16x32_bf16 v[122:125], v[148:151], v[180:183], v[122:125]
	v_mfma_f32_16x16x32_bf16 v[118:121], v[140:143], v[188:191], v[118:121]
	v_mfma_f32_16x16x32_bf16 v[114:117], v[148:151], v[188:191], v[114:117]
	v_mfma_f32_16x16x32_bf16 v[94:97], v[140:143], v[196:199], v[94:97]
	v_mfma_f32_16x16x32_bf16 v[90:93], v[148:151], v[196:199], v[90:93]
	v_mfma_f32_16x16x32_bf16 v[78:81], v[140:143], v[204:207], v[78:81]
	v_mfma_f32_16x16x32_bf16 v[74:77], v[148:151], v[204:207], v[74:77]
	v_mfma_f32_16x16x32_bf16 v[126:129], v[144:147], v[184:187], v[126:129]
	v_mfma_f32_16x16x32_bf16 v[122:125], v[152:155], v[184:187], v[122:125]
	v_mfma_f32_16x16x32_bf16 v[118:121], v[144:147], v[192:195], v[118:121]
	v_mfma_f32_16x16x32_bf16 v[114:117], v[152:155], v[192:195], v[114:117]
	v_mfma_f32_16x16x32_bf16 v[94:97], v[144:147], v[200:203], v[94:97]
	v_mfma_f32_16x16x32_bf16 v[90:93], v[152:155], v[200:203], v[90:93]
	v_mfma_f32_16x16x32_bf16 v[78:81], v[144:147], v[208:211], v[78:81]
	v_mfma_f32_16x16x32_bf16 v[74:77], v[152:155], v[208:211], v[74:77]
	s_setprio 0
	s_setprio 1
	v_mfma_f32_16x16x32_bf16 v[110:113], v[156:159], v[180:183], v[110:113]
	v_mfma_f32_16x16x32_bf16 v[106:109], v[168:171], v[180:183], v[106:109]
	v_mfma_f32_16x16x32_bf16 v[102:105], v[156:159], v[188:191], v[102:105]
	v_mfma_f32_16x16x32_bf16 v[98:101], v[168:171], v[188:191], v[98:101]
	v_mfma_f32_16x16x32_bf16 v[86:89], v[156:159], v[196:199], v[86:89]
	v_mfma_f32_16x16x32_bf16 v[82:85], v[168:171], v[196:199], v[82:85]
	v_mfma_f32_16x16x32_bf16 v[70:73], v[156:159], v[204:207], v[70:73]
	v_mfma_f32_16x16x32_bf16 v[66:69], v[168:171], v[204:207], v[66:69]
	v_mfma_f32_16x16x32_bf16 v[110:113], v[164:167], v[184:187], v[110:113]
	v_mfma_f32_16x16x32_bf16 v[106:109], v[172:175], v[184:187], v[106:109]
	v_mfma_f32_16x16x32_bf16 v[102:105], v[164:167], v[192:195], v[102:105]
	v_mfma_f32_16x16x32_bf16 v[98:101], v[172:175], v[192:195], v[98:101]
	v_mfma_f32_16x16x32_bf16 v[86:89], v[164:167], v[200:203], v[86:89]
	v_mfma_f32_16x16x32_bf16 v[82:85], v[172:175], v[200:203], v[82:85]
	v_mfma_f32_16x16x32_bf16 v[70:73], v[164:167], v[208:211], v[70:73]
	v_mfma_f32_16x16x32_bf16 v[66:69], v[172:175], v[208:211], v[66:69]
	s_setprio 2
	s_barrier
	s_add_i32 s10, s64, s28
	v_lshl_add_u64 v[176:177], v[176:177], 0, s[94:95]
	s_mov_b32 m0, s10
	ds_read_b128 v[180:183], v163 offset:49152
	ds_read_b128 v[184:187], v163 offset:50176
	ds_read_b128 v[188:191], v163 offset:51200
	ds_read_b128 v[192:195], v163 offset:52224
	ds_read_b128 v[196:199], v163 offset:53248
	ds_read_b128 v[200:203], v163 offset:54272
	ds_read_b128 v[204:207], v163 offset:55296
	ds_read_b128 v[208:211], v163 offset:56320
	global_load_lds_dwordx4 v[176:177], off
	s_add_i32 m0, s10, 0x2000
	s_add_u32 s10, s42, 0x20080
	v_lshl_add_u64 v[176:177], v[178:179], 0, s[94:95]
	s_addc_u32 s11, s43, 0
	s_add_i32 s42, s65, s28
	global_load_lds_dwordx4 v[176:177], off
	v_lshl_add_u64 v[176:177], s[10:11], 0, v[0:1]
	s_mov_b32 m0, s42
	s_nop 0
	global_load_lds_dwordx4 v[176:177], off
	v_lshl_add_u64 v[176:177], s[10:11], 0, v[130:131]
	s_add_i32 m0, s42, 0x2000
	s_nop 0
	global_load_lds_dwordx4 v[176:177], off
	v_lshl_add_u64 v[176:177], v[212:213], 0, s[94:95]
	s_mov_b32 m0, s58
	s_nop 0
	global_load_lds_dwordx4 v[176:177], off
	v_lshl_add_u64 v[176:177], v[214:215], 0, s[94:95]
	s_mov_b32 m0, s59
	s_nop 0
	global_load_lds_dwordx4 v[176:177], off
	s_waitcnt vmcnt(8)
	s_waitcnt lgkmcnt(0)
	s_barrier
	s_setprio 1
	s_waitcnt lgkmcnt(0)
	v_mfma_f32_16x16x32_bf16 v[62:65], v[140:143], v[180:183], v[62:65]
	v_mfma_f32_16x16x32_bf16 v[58:61], v[148:151], v[180:183], v[58:61]
	v_mfma_f32_16x16x32_bf16 v[46:49], v[140:143], v[188:191], v[46:49]
	v_mfma_f32_16x16x32_bf16 v[42:45], v[148:151], v[188:191], v[42:45]
	v_mfma_f32_16x16x32_bf16 v[30:33], v[140:143], v[196:199], v[30:33]
	v_mfma_f32_16x16x32_bf16 v[26:29], v[148:151], v[196:199], v[26:29]
	v_mfma_f32_16x16x32_bf16 v[14:17], v[140:143], v[204:207], v[14:17]
	v_mfma_f32_16x16x32_bf16 v[10:13], v[148:151], v[204:207], v[10:13]
	v_mfma_f32_16x16x32_bf16 v[62:65], v[144:147], v[184:187], v[62:65]
	v_mfma_f32_16x16x32_bf16 v[58:61], v[152:155], v[184:187], v[58:61]
	v_mfma_f32_16x16x32_bf16 v[46:49], v[144:147], v[192:195], v[46:49]
	v_mfma_f32_16x16x32_bf16 v[42:45], v[152:155], v[192:195], v[42:45]
	v_mfma_f32_16x16x32_bf16 v[30:33], v[144:147], v[200:203], v[30:33]
	v_mfma_f32_16x16x32_bf16 v[26:29], v[152:155], v[200:203], v[26:29]
	v_mfma_f32_16x16x32_bf16 v[14:17], v[144:147], v[208:211], v[14:17]
	v_mfma_f32_16x16x32_bf16 v[10:13], v[152:155], v[208:211], v[10:13]
	s_setprio 0
	s_setprio 1
	v_mfma_f32_16x16x32_bf16 v[54:57], v[156:159], v[180:183], v[54:57]
	v_mfma_f32_16x16x32_bf16 v[50:53], v[168:171], v[180:183], v[50:53]
	v_mfma_f32_16x16x32_bf16 v[38:41], v[156:159], v[188:191], v[38:41]
	v_mfma_f32_16x16x32_bf16 v[34:37], v[168:171], v[188:191], v[34:37]
	v_mfma_f32_16x16x32_bf16 v[22:25], v[156:159], v[196:199], v[22:25]
	v_mfma_f32_16x16x32_bf16 v[18:21], v[168:171], v[196:199], v[18:21]
	v_mfma_f32_16x16x32_bf16 v[6:9], v[156:159], v[204:207], v[6:9]
	v_mfma_f32_16x16x32_bf16 v[2:5], v[168:171], v[204:207], v[2:5]
	v_mfma_f32_16x16x32_bf16 v[54:57], v[164:167], v[184:187], v[54:57]
	v_mfma_f32_16x16x32_bf16 v[50:53], v[172:175], v[184:187], v[50:53]
	v_mfma_f32_16x16x32_bf16 v[38:41], v[164:167], v[192:195], v[38:41]
	v_mfma_f32_16x16x32_bf16 v[34:37], v[172:175], v[192:195], v[34:37]
	v_mfma_f32_16x16x32_bf16 v[22:25], v[164:167], v[200:203], v[22:25]
	v_mfma_f32_16x16x32_bf16 v[18:21], v[172:175], v[200:203], v[18:21]
	v_mfma_f32_16x16x32_bf16 v[6:9], v[164:167], v[208:211], v[6:9]
	v_mfma_f32_16x16x32_bf16 v[2:5], v[172:175], v[208:211], v[2:5]
	s_setprio 2
	s_add_i32 s72, s72, 2
	s_add_u32 s70, s70, 0x100
	s_addc_u32 s71, s71, 0
	s_add_u32 s12, s12, 0x100
	s_addc_u32 s13, s13, 0
	s_cmp_gt_u32 s72, 5
	s_barrier
	s_cbranch_scc0 .LBB0_341
	s_and_b64 vcc, exec, s[20:21]
	s_cbranch_vccz .LBB0_344
	s_barrier

.LBB0_685:
	s_add_u32 s36, s12, s38
	s_addc_u32 s42, s13, s39
	s_add_u32 s36, s36, 0x100
	s_addc_u32 s42, s42, 0
	s_add_u32 s62, s35, s38
	s_addc_u32 s43, s63, s39
	s_cmpk_eq_i32 s38, 0xf00
	s_cselect_b32 s45, s27, s42
	s_cselect_b32 s44, s60, s36
	s_cselect_b32 s43, s21, s43
	s_cselect_b32 s42, s61, s62
	s_add_i32 s36, 0, 0x10000
	v_add_u32_e32 v0, s36, v188
	s_add_i32 s62, 0, 0x14000
	ds_read_b128 v[138:141], v0
	ds_read_b128 v[142:145], v0 offset:1024
	ds_read_b128 v[146:149], v0 offset:2048
	ds_read_b128 v[150:153], v0 offset:3072
	v_add_u32_e32 v0, s62, v188
	ds_read_b128 v[170:173], v0
	ds_read_b128 v[174:177], v0 offset:1024
	ds_read_b128 v[178:181], v0 offset:2048
	ds_read_b128 v[182:185], v0 offset:3072
	v_lshl_add_u64 v[2:3], v[136:137], 0, s[38:39]
	s_add_i32 m0, s33, 0xc000
	ds_read_b128 v[190:193], v189
	ds_read_b128 v[194:197], v189 offset:1024
	ds_read_b128 v[198:201], v189 offset:2048
	ds_read_b128 v[202:205], v189 offset:3072
	ds_read_b128 v[206:209], v189 offset:4096
	ds_read_b128 v[210:213], v189 offset:5120
	ds_read_b128 v[214:217], v189 offset:6144
	ds_read_b128 v[218:221], v189 offset:7168
	global_load_lds_dwordx4 v[2:3], off
	v_lshl_add_u64 v[2:3], v[134:135], 0, s[38:39]
	s_add_i32 m0, s33, 0xe000
	s_nop 0
	global_load_lds_dwordx4 v[2:3], off
	s_waitcnt vmcnt(8)
	s_waitcnt lgkmcnt(0)
	s_barrier
	s_setprio 1
	s_waitcnt lgkmcnt(0)
	v_mfma_f32_16x16x32_bf16 v[128:131], v[138:141], v[190:193], v[128:131]
	v_mfma_f32_16x16x32_bf16 v[124:127], v[146:149], v[190:193], v[124:127]
	v_mfma_f32_16x16x32_bf16 v[112:115], v[138:141], v[198:201], v[112:115]
	v_mfma_f32_16x16x32_bf16 v[108:111], v[146:149], v[198:201], v[108:111]
	v_mfma_f32_16x16x32_bf16 v[96:99], v[138:141], v[206:209], v[96:99]
	v_mfma_f32_16x16x32_bf16 v[92:95], v[146:149], v[206:209], v[92:95]
	v_mfma_f32_16x16x32_bf16 v[80:83], v[138:141], v[214:217], v[80:83]
	v_mfma_f32_16x16x32_bf16 v[76:79], v[146:149], v[214:217], v[76:79]
	v_mfma_f32_16x16x32_bf16 v[128:131], v[142:145], v[194:197], v[128:131]
	v_mfma_f32_16x16x32_bf16 v[124:127], v[150:153], v[194:197], v[124:127]
	v_mfma_f32_16x16x32_bf16 v[112:115], v[142:145], v[202:205], v[112:115]
	v_mfma_f32_16x16x32_bf16 v[108:111], v[150:153], v[202:205], v[108:111]
	v_mfma_f32_16x16x32_bf16 v[96:99], v[142:145], v[210:213], v[96:99]
	v_mfma_f32_16x16x32_bf16 v[92:95], v[150:153], v[210:213], v[92:95]
	v_mfma_f32_16x16x32_bf16 v[80:83], v[142:145], v[218:221], v[80:83]
	v_mfma_f32_16x16x32_bf16 v[76:79], v[150:153], v[218:221], v[76:79]
	s_setprio 0
	s_setprio 1
	v_mfma_f32_16x16x32_bf16 v[120:123], v[170:173], v[190:193], v[120:123]
	v_mfma_f32_16x16x32_bf16 v[116:119], v[178:181], v[190:193], v[116:119]
	v_mfma_f32_16x16x32_bf16 v[104:107], v[170:173], v[198:201], v[104:107]
	v_mfma_f32_16x16x32_bf16 v[100:103], v[178:181], v[198:201], v[100:103]
	v_mfma_f32_16x16x32_bf16 v[88:91], v[170:173], v[206:209], v[88:91]
	v_mfma_f32_16x16x32_bf16 v[84:87], v[178:181], v[206:209], v[84:87]
	v_mfma_f32_16x16x32_bf16 v[72:75], v[170:173], v[214:217], v[72:75]
	v_mfma_f32_16x16x32_bf16 v[68:71], v[178:181], v[214:217], v[68:71]
	v_mfma_f32_16x16x32_bf16 v[120:123], v[174:177], v[194:197], v[120:123]
	v_mfma_f32_16x16x32_bf16 v[116:119], v[182:185], v[194:197], v[116:119]
	v_mfma_f32_16x16x32_bf16 v[104:107], v[174:177], v[202:205], v[104:107]
	v_mfma_f32_16x16x32_bf16 v[100:103], v[182:185], v[202:205], v[100:103]
	v_mfma_f32_16x16x32_bf16 v[88:91], v[174:177], v[210:213], v[88:91]
	v_mfma_f32_16x16x32_bf16 v[84:87], v[182:185], v[210:213], v[84:87]
	v_mfma_f32_16x16x32_bf16 v[72:75], v[174:177], v[218:221], v[72:75]
	v_mfma_f32_16x16x32_bf16 v[68:71], v[182:185], v[218:221], v[68:71]
	s_setprio 2
	s_barrier
	s_add_i32 s36, s36, s41
	v_lshl_add_u64 v[154:155], s[42:43], 0, v[160:161]
	s_mov_b32 m0, s36
	ds_read_b128 v[190:193], v189 offset:16384
	ds_read_b128 v[194:197], v189 offset:17408
	ds_read_b128 v[198:201], v189 offset:18432
	ds_read_b128 v[202:205], v189 offset:19456
	ds_read_b128 v[206:209], v189 offset:20480
	ds_read_b128 v[210:213], v189 offset:21504
	ds_read_b128 v[214:217], v189 offset:22528
	ds_read_b128 v[218:221], v189 offset:23552
	global_load_lds_dwordx4 v[154:155], off
	s_add_i32 m0, s36, 0x2000
	s_add_u32 s66, s42, 0x80000
	v_lshl_add_u64 v[222:223], s[42:43], 0, v[156:157]
	s_addc_u32 s67, s43, 0
	s_add_i32 s36, s62, s41
	global_load_lds_dwordx4 v[222:223], off
	v_lshl_add_u64 v[2:3], s[66:67], 0, v[160:161]
	s_mov_b32 m0, s36
	v_lshl_add_u64 v[224:225], s[44:45], 0, v[162:163]
	global_load_lds_dwordx4 v[2:3], off
	v_lshl_add_u64 v[2:3], s[66:67], 0, v[156:157]
	s_add_i32 m0, s36, 0x2000
	v_lshl_add_u64 v[226:227], s[44:45], 0, v[158:159]
	global_load_lds_dwordx4 v[2:3], off
	s_mov_b32 m0, s33
	s_nop 0
	global_load_lds_dwordx4 v[224:225], off
	s_mov_b32 m0, s56
	s_nop 0
	global_load_lds_dwordx4 v[226:227], off
	s_waitcnt vmcnt(8)
	s_waitcnt lgkmcnt(0)
	s_barrier
	s_setprio 1
	s_waitcnt lgkmcnt(0)
	v_mfma_f32_16x16x32_bf16 v[64:67], v[138:141], v[190:193], v[64:67]
	v_mfma_f32_16x16x32_bf16 v[60:63], v[146:149], v[190:193], v[60:63]
	v_mfma_f32_16x16x32_bf16 v[48:51], v[138:141], v[198:201], v[48:51]
	v_mfma_f32_16x16x32_bf16 v[44:47], v[146:149], v[198:201], v[44:47]
	v_mfma_f32_16x16x32_bf16 v[32:35], v[138:141], v[206:209], v[32:35]
	v_mfma_f32_16x16x32_bf16 v[28:31], v[146:149], v[206:209], v[28:31]
	v_mfma_f32_16x16x32_bf16 v[16:19], v[138:141], v[214:217], v[16:19]
	v_mfma_f32_16x16x32_bf16 v[12:15], v[146:149], v[214:217], v[12:15]
	v_mfma_f32_16x16x32_bf16 v[64:67], v[142:145], v[194:197], v[64:67]
	v_mfma_f32_16x16x32_bf16 v[60:63], v[150:153], v[194:197], v[60:63]
	v_mfma_f32_16x16x32_bf16 v[48:51], v[142:145], v[202:205], v[48:51]
	v_mfma_f32_16x16x32_bf16 v[44:47], v[150:153], v[202:205], v[44:47]
	v_mfma_f32_16x16x32_bf16 v[32:35], v[142:145], v[210:213], v[32:35]
	v_mfma_f32_16x16x32_bf16 v[28:31], v[150:153], v[210:213], v[28:31]
	v_mfma_f32_16x16x32_bf16 v[16:19], v[142:145], v[218:221], v[16:19]
	v_mfma_f32_16x16x32_bf16 v[12:15], v[150:153], v[218:221], v[12:15]
	s_setprio 0
	s_setprio 1
	v_mfma_f32_16x16x32_bf16 v[56:59], v[170:173], v[190:193], v[56:59]
	v_mfma_f32_16x16x32_bf16 v[52:55], v[178:181], v[190:193], v[52:55]
	v_mfma_f32_16x16x32_bf16 v[40:43], v[170:173], v[198:201], v[40:43]
	v_mfma_f32_16x16x32_bf16 v[36:39], v[178:181], v[198:201], v[36:39]
	v_mfma_f32_16x16x32_bf16 v[24:27], v[170:173], v[206:209], v[24:27]
	v_mfma_f32_16x16x32_bf16 v[20:23], v[178:181], v[206:209], v[20:23]
	v_mfma_f32_16x16x32_bf16 v[8:11], v[170:173], v[214:217], v[8:11]
	v_mfma_f32_16x16x32_bf16 v[2:5], v[178:181], v[214:217], v[4:7]
	v_mfma_f32_16x16x32_bf16 v[56:59], v[174:177], v[194:197], v[56:59]
	v_mfma_f32_16x16x32_bf16 v[52:55], v[182:185], v[194:197], v[52:55]
	v_mfma_f32_16x16x32_bf16 v[40:43], v[174:177], v[202:205], v[40:43]
	v_mfma_f32_16x16x32_bf16 v[36:39], v[182:185], v[202:205], v[36:39]
	v_mfma_f32_16x16x32_bf16 v[24:27], v[174:177], v[210:213], v[24:27]
	v_mfma_f32_16x16x32_bf16 v[20:23], v[182:185], v[210:213], v[20:23]
	v_mfma_f32_16x16x32_bf16 v[8:11], v[174:177], v[218:221], v[8:11]
	v_mfma_f32_16x16x32_bf16 v[2:5], v[182:185], v[218:221], v[2:5]
	s_setprio 2
	s_barrier
	s_add_i32 s36, 0, 0x18000
	v_add_u32_e32 v0, s36, v188
	s_add_i32 s62, 0, 0x1c000
	ds_read_b128 v[138:141], v0
	ds_read_b128 v[142:145], v0 offset:1024
	ds_read_b128 v[146:149], v0 offset:2048
	ds_read_b128 v[150:153], v0 offset:3072
	v_add_u32_e32 v0, s62, v188
	ds_read_b128 v[170:173], v0
	ds_read_b128 v[174:177], v0 offset:1024
	ds_read_b128 v[178:181], v0 offset:2048
	ds_read_b128 v[182:185], v0 offset:3072
	s_add_u32 s44, s44, 0x80000
	s_addc_u32 s45, s45, 0
	s_mov_b32 m0, s57
	v_lshl_add_u64 v[6:7], s[44:45], 0, v[162:163]
	ds_read_b128 v[190:193], v189 offset:32768
	ds_read_b128 v[194:197], v189 offset:33792
	ds_read_b128 v[198:201], v189 offset:34816
	ds_read_b128 v[202:205], v189 offset:35840
	ds_read_b128 v[206:209], v189 offset:36864
	ds_read_b128 v[210:213], v189 offset:37888
	ds_read_b128 v[214:217], v189 offset:38912
	ds_read_b128 v[218:221], v189 offset:39936
	global_load_lds_dwordx4 v[6:7], off
	v_lshl_add_u64 v[6:7], s[44:45], 0, v[158:159]
	s_mov_b32 m0, s59
	s_nop 0
	global_load_lds_dwordx4 v[6:7], off
	s_waitcnt vmcnt(8)
	s_waitcnt lgkmcnt(0)
	s_barrier
	s_setprio 1
	s_waitcnt lgkmcnt(0)
	v_mfma_f32_16x16x32_bf16 v[128:131], v[138:141], v[190:193], v[128:131]
	v_mfma_f32_16x16x32_bf16 v[124:127], v[146:149], v[190:193], v[124:127]
	v_mfma_f32_16x16x32_bf16 v[112:115], v[138:141], v[198:201], v[112:115]
	v_mfma_f32_16x16x32_bf16 v[108:111], v[146:149], v[198:201], v[108:111]
	v_mfma_f32_16x16x32_bf16 v[96:99], v[138:141], v[206:209], v[96:99]
	v_mfma_f32_16x16x32_bf16 v[92:95], v[146:149], v[206:209], v[92:95]
	v_mfma_f32_16x16x32_bf16 v[80:83], v[138:141], v[214:217], v[80:83]
	v_mfma_f32_16x16x32_bf16 v[76:79], v[146:149], v[214:217], v[76:79]
	v_mfma_f32_16x16x32_bf16 v[128:131], v[142:145], v[194:197], v[128:131]
	v_mfma_f32_16x16x32_bf16 v[124:127], v[150:153], v[194:197], v[124:127]
	v_mfma_f32_16x16x32_bf16 v[112:115], v[142:145], v[202:205], v[112:115]
	v_mfma_f32_16x16x32_bf16 v[108:111], v[150:153], v[202:205], v[108:111]
	v_mfma_f32_16x16x32_bf16 v[96:99], v[142:145], v[210:213], v[96:99]
	v_mfma_f32_16x16x32_bf16 v[92:95], v[150:153], v[210:213], v[92:95]
	v_mfma_f32_16x16x32_bf16 v[80:83], v[142:145], v[218:221], v[80:83]
	v_mfma_f32_16x16x32_bf16 v[76:79], v[150:153], v[218:221], v[76:79]
	s_setprio 0
	s_setprio 1
	v_mfma_f32_16x16x32_bf16 v[120:123], v[170:173], v[190:193], v[120:123]
	v_mfma_f32_16x16x32_bf16 v[116:119], v[178:181], v[190:193], v[116:119]
	v_mfma_f32_16x16x32_bf16 v[104:107], v[170:173], v[198:201], v[104:107]
	v_mfma_f32_16x16x32_bf16 v[100:103], v[178:181], v[198:201], v[100:103]
	v_mfma_f32_16x16x32_bf16 v[88:91], v[170:173], v[206:209], v[88:91]
	v_mfma_f32_16x16x32_bf16 v[84:87], v[178:181], v[206:209], v[84:87]
	v_mfma_f32_16x16x32_bf16 v[72:75], v[170:173], v[214:217], v[72:75]
	v_mfma_f32_16x16x32_bf16 v[68:71], v[178:181], v[214:217], v[68:71]
	v_mfma_f32_16x16x32_bf16 v[120:123], v[174:177], v[194:197], v[120:123]
	v_mfma_f32_16x16x32_bf16 v[116:119], v[182:185], v[194:197], v[116:119]
	v_mfma_f32_16x16x32_bf16 v[104:107], v[174:177], v[202:205], v[104:107]
	v_mfma_f32_16x16x32_bf16 v[100:103], v[182:185], v[202:205], v[100:103]
	v_mfma_f32_16x16x32_bf16 v[88:91], v[174:177], v[210:213], v[88:91]
	v_mfma_f32_16x16x32_bf16 v[84:87], v[182:185], v[210:213], v[84:87]
	v_mfma_f32_16x16x32_bf16 v[72:75], v[174:177], v[218:221], v[72:75]
	v_mfma_f32_16x16x32_bf16 v[68:71], v[182:185], v[218:221], v[68:71]
	s_setprio 2
	s_barrier
	s_add_i32 s36, s36, s41
	v_lshl_add_u64 v[6:7], v[154:155], 0, s[94:95]
	s_mov_b32 m0, s36
	ds_read_b128 v[190:193], v189 offset:49152
	ds_read_b128 v[194:197], v189 offset:50176
	ds_read_b128 v[198:201], v189 offset:51200
	ds_read_b128 v[202:205], v189 offset:52224
	ds_read_b128 v[206:209], v189 offset:53248
	ds_read_b128 v[210:213], v189 offset:54272
	ds_read_b128 v[214:217], v189 offset:55296
	ds_read_b128 v[218:221], v189 offset:56320
	global_load_lds_dwordx4 v[6:7], off
	s_add_i32 m0, s36, 0x2000
	s_add_u32 s42, s42, 0x80080
	v_lshl_add_u64 v[6:7], v[222:223], 0, s[94:95]
	s_addc_u32 s43, s43, 0
	s_add_i32 s36, s62, s41
	global_load_lds_dwordx4 v[6:7], off
	v_lshl_add_u64 v[6:7], s[42:43], 0, v[160:161]
	s_mov_b32 m0, s36
	s_nop 0
	global_load_lds_dwordx4 v[6:7], off
	v_lshl_add_u64 v[6:7], s[42:43], 0, v[156:157]
	s_add_i32 m0, s36, 0x2000
	s_nop 0
	global_load_lds_dwordx4 v[6:7], off
	v_lshl_add_u64 v[6:7], v[224:225], 0, s[94:95]
	s_mov_b32 m0, s48
	s_nop 0
	global_load_lds_dwordx4 v[6:7], off
	v_lshl_add_u64 v[6:7], v[226:227], 0, s[94:95]
	s_mov_b32 m0, s52
	s_nop 0
	global_load_lds_dwordx4 v[6:7], off
	s_waitcnt vmcnt(8)
	s_waitcnt lgkmcnt(0)
	s_barrier
	s_setprio 1
	s_waitcnt lgkmcnt(0)
	v_mfma_f32_16x16x32_bf16 v[64:67], v[138:141], v[190:193], v[64:67]
	v_mfma_f32_16x16x32_bf16 v[60:63], v[146:149], v[190:193], v[60:63]
	v_mfma_f32_16x16x32_bf16 v[48:51], v[138:141], v[198:201], v[48:51]
	v_mfma_f32_16x16x32_bf16 v[44:47], v[146:149], v[198:201], v[44:47]
	v_mfma_f32_16x16x32_bf16 v[32:35], v[138:141], v[206:209], v[32:35]
	v_mfma_f32_16x16x32_bf16 v[28:31], v[146:149], v[206:209], v[28:31]
	v_mfma_f32_16x16x32_bf16 v[16:19], v[138:141], v[214:217], v[16:19]
	v_mfma_f32_16x16x32_bf16 v[12:15], v[146:149], v[214:217], v[12:15]
	v_mfma_f32_16x16x32_bf16 v[64:67], v[142:145], v[194:197], v[64:67]
	v_mfma_f32_16x16x32_bf16 v[60:63], v[150:153], v[194:197], v[60:63]
	v_mfma_f32_16x16x32_bf16 v[48:51], v[142:145], v[202:205], v[48:51]
	v_mfma_f32_16x16x32_bf16 v[44:47], v[150:153], v[202:205], v[44:47]
	v_mfma_f32_16x16x32_bf16 v[32:35], v[142:145], v[210:213], v[32:35]
	v_mfma_f32_16x16x32_bf16 v[28:31], v[150:153], v[210:213], v[28:31]
	v_mfma_f32_16x16x32_bf16 v[16:19], v[142:145], v[218:221], v[16:19]
	v_mfma_f32_16x16x32_bf16 v[12:15], v[150:153], v[218:221], v[12:15]
	s_setprio 0
	s_setprio 1
	v_mfma_f32_16x16x32_bf16 v[56:59], v[170:173], v[190:193], v[56:59]
	v_mfma_f32_16x16x32_bf16 v[52:55], v[178:181], v[190:193], v[52:55]
	v_mfma_f32_16x16x32_bf16 v[40:43], v[170:173], v[198:201], v[40:43]
	v_mfma_f32_16x16x32_bf16 v[36:39], v[178:181], v[198:201], v[36:39]
	v_mfma_f32_16x16x32_bf16 v[24:27], v[170:173], v[206:209], v[24:27]
	v_mfma_f32_16x16x32_bf16 v[20:23], v[178:181], v[206:209], v[20:23]
	v_mfma_f32_16x16x32_bf16 v[6:9], v[170:173], v[214:217], v[8:11]
	v_mfma_f32_16x16x32_bf16 v[2:5], v[178:181], v[214:217], v[2:5]
	v_mfma_f32_16x16x32_bf16 v[56:59], v[174:177], v[194:197], v[56:59]
	v_mfma_f32_16x16x32_bf16 v[52:55], v[182:185], v[194:197], v[52:55]
	v_mfma_f32_16x16x32_bf16 v[40:43], v[174:177], v[202:205], v[40:43]
	v_mfma_f32_16x16x32_bf16 v[36:39], v[182:185], v[202:205], v[36:39]
	v_mfma_f32_16x16x32_bf16 v[24:27], v[174:177], v[210:213], v[24:27]
	v_mfma_f32_16x16x32_bf16 v[20:23], v[182:185], v[210:213], v[20:23]
	v_mfma_f32_16x16x32_bf16 v[8:11], v[174:177], v[218:221], v[6:9]
	v_mfma_f32_16x16x32_bf16 v[4:7], v[182:185], v[218:221], v[2:5]
	s_setprio 2
	s_add_i32 s64, s64, 2
	s_add_u32 s38, s38, 0x100
	s_addc_u32 s39, s39, 0
	s_cmp_gt_u32 s64, 29
	s_barrier
	s_cbranch_scc1 .LBB0_688

.LBB0_773:
	s_add_u32 s6, s12, 0xfff80080
	s_addc_u32 s7, s13, -1
	s_add_i32 s19, 0, 0x10000
	s_cmp_eq_u32 s18, 28
	s_cselect_b32 s15, s61, s7
	s_cselect_b32 s14, vcc_lo, s6
	s_cselect_b32 s7, s35, s17
	s_cselect_b32 s6, vcc_hi, s16
	s_add_i32 s80, 0, 0x14000
	v_add_u32_e32 v142, s19, v208
	v_add_u32_e32 v158, s80, v208
	ds_read_b128 v[130:133], v142
	ds_read_b128 v[134:137], v142 offset:1024
	ds_read_b128 v[138:141], v142 offset:2048
	ds_read_b128 v[142:145], v142 offset:3072
	ds_read_b128 v[146:149], v158
	ds_read_b128 v[150:153], v158 offset:1024
	ds_read_b128 v[154:157], v158 offset:2048
	ds_read_b128 v[158:161], v158 offset:3072
	v_lshl_add_u64 v[170:171], s[12:13], 0, v[184:185]
	s_add_i32 m0, s33, 0xc000
	ds_read_b128 v[162:165], v209
	ds_read_b128 v[166:169], v209 offset:1024
	ds_read_b128 v[176:179], v209 offset:2048
	ds_read_b128 v[186:189], v209 offset:3072
	ds_read_b128 v[190:193], v209 offset:4096
	ds_read_b128 v[194:197], v209 offset:5120
	ds_read_b128 v[198:201], v209 offset:6144
	ds_read_b128 v[202:205], v209 offset:7168
	global_load_lds_dwordx4 v[170:171], off
	v_lshl_add_u64 v[170:171], s[12:13], 0, v[182:183]
	s_add_i32 m0, s33, 0xe000
	s_nop 0
	global_load_lds_dwordx4 v[170:171], off
	s_waitcnt vmcnt(8)
	s_waitcnt lgkmcnt(0)
	s_barrier
	s_setprio 1
	s_waitcnt lgkmcnt(0)
	v_mfma_f32_16x16x32_bf16 v[122:125], v[130:133], v[162:165], v[122:125]
	v_mfma_f32_16x16x32_bf16 v[90:93], v[138:141], v[162:165], v[90:93]
	v_mfma_f32_16x16x32_bf16 v[110:113], v[130:133], v[176:179], v[110:113]
	v_mfma_f32_16x16x32_bf16 v[46:49], v[138:141], v[176:179], v[46:49]
	v_mfma_f32_16x16x32_bf16 v[106:109], v[130:133], v[190:193], v[106:109]
	v_mfma_f32_16x16x32_bf16 v[42:45], v[138:141], v[190:193], v[42:45]
	v_mfma_f32_16x16x32_bf16 v[126:129], v[130:133], v[198:201], v[126:129]
	v_mfma_f32_16x16x32_bf16 v[54:57], v[138:141], v[198:201], v[54:57]
	v_mfma_f32_16x16x32_bf16 v[122:125], v[134:137], v[166:169], v[122:125]
	v_mfma_f32_16x16x32_bf16 v[90:93], v[142:145], v[166:169], v[90:93]
	v_mfma_f32_16x16x32_bf16 v[110:113], v[134:137], v[186:189], v[110:113]
	v_mfma_f32_16x16x32_bf16 v[46:49], v[142:145], v[186:189], v[46:49]
	v_mfma_f32_16x16x32_bf16 v[106:109], v[134:137], v[194:197], v[106:109]
	v_mfma_f32_16x16x32_bf16 v[42:45], v[142:145], v[194:197], v[42:45]
	v_mfma_f32_16x16x32_bf16 v[126:129], v[134:137], v[202:205], v[126:129]
	v_mfma_f32_16x16x32_bf16 v[54:57], v[142:145], v[202:205], v[54:57]
	s_setprio 0
	s_setprio 1
	v_mfma_f32_16x16x32_bf16 v[114:117], v[146:149], v[162:165], v[114:117]
	v_mfma_f32_16x16x32_bf16 v[94:97], v[154:157], v[162:165], v[94:97]
	v_mfma_f32_16x16x32_bf16 v[102:105], v[146:149], v[176:179], v[102:105]
	v_mfma_f32_16x16x32_bf16 v[38:41], v[154:157], v[176:179], v[38:41]
	v_mfma_f32_16x16x32_bf16 v[98:101], v[146:149], v[190:193], v[98:101]
	v_mfma_f32_16x16x32_bf16 v[34:37], v[154:157], v[190:193], v[34:37]
	v_mfma_f32_16x16x32_bf16 v[118:121], v[146:149], v[198:201], v[118:121]
	v_mfma_f32_16x16x32_bf16 v[50:53], v[154:157], v[198:201], v[50:53]
	v_mfma_f32_16x16x32_bf16 v[114:117], v[150:153], v[166:169], v[114:117]
	v_mfma_f32_16x16x32_bf16 v[94:97], v[158:161], v[166:169], v[94:97]
	v_mfma_f32_16x16x32_bf16 v[102:105], v[150:153], v[186:189], v[102:105]
	v_mfma_f32_16x16x32_bf16 v[38:41], v[158:161], v[186:189], v[38:41]
	v_mfma_f32_16x16x32_bf16 v[98:101], v[150:153], v[194:197], v[98:101]
	v_mfma_f32_16x16x32_bf16 v[34:37], v[158:161], v[194:197], v[34:37]
	v_mfma_f32_16x16x32_bf16 v[118:121], v[150:153], v[202:205], v[118:121]
	v_mfma_f32_16x16x32_bf16 v[50:53], v[158:161], v[202:205], v[50:53]
	s_setprio 2
	s_barrier
	s_add_i32 s19, s19, s41
	v_lshl_add_u64 v[170:171], s[6:7], 0, v[0:1]
	s_mov_b32 m0, s19
	ds_read_b128 v[162:165], v209 offset:16384
	ds_read_b128 v[166:169], v209 offset:17408
	ds_read_b128 v[176:179], v209 offset:18432
	ds_read_b128 v[186:189], v209 offset:19456
	ds_read_b128 v[190:193], v209 offset:20480
	ds_read_b128 v[194:197], v209 offset:21504
	ds_read_b128 v[198:201], v209 offset:22528
	ds_read_b128 v[202:205], v209 offset:23552
	global_load_lds_dwordx4 v[170:171], off
	s_add_i32 m0, s19, 0x2000
	s_add_u32 s24, s6, 0x80000
	v_lshl_add_u64 v[210:211], s[6:7], 0, v[172:173]
	s_addc_u32 s25, s7, 0
	s_add_i32 s19, s80, s41
	global_load_lds_dwordx4 v[210:211], off
	v_lshl_add_u64 v[212:213], s[24:25], 0, v[0:1]
	s_mov_b32 m0, s19
	v_lshl_add_u64 v[214:215], s[14:15], 0, v[174:175]
	global_load_lds_dwordx4 v[212:213], off
	v_lshl_add_u64 v[212:213], s[24:25], 0, v[172:173]
	s_add_i32 m0, s19, 0x2000
	s_nop 0
	global_load_lds_dwordx4 v[212:213], off
	v_lshl_add_u64 v[212:213], s[14:15], 0, v[180:181]
	s_mov_b32 m0, s33
	s_nop 0
	global_load_lds_dwordx4 v[212:213], off
	s_mov_b32 m0, s59
	s_nop 0
	global_load_lds_dwordx4 v[214:215], off
	s_waitcnt vmcnt(8)
	s_waitcnt lgkmcnt(0)
	s_barrier
	s_setprio 1
	s_waitcnt lgkmcnt(0)
	v_mfma_f32_16x16x32_bf16 v[78:81], v[130:133], v[162:165], v[78:81]
	v_mfma_f32_16x16x32_bf16 v[22:25], v[138:141], v[162:165], v[22:25]
	v_mfma_f32_16x16x32_bf16 v[70:73], v[130:133], v[176:179], v[70:73]
	v_mfma_f32_16x16x32_bf16 v[18:21], v[138:141], v[176:179], v[18:21]
	v_mfma_f32_16x16x32_bf16 v[66:69], v[130:133], v[190:193], v[66:69]
	v_mfma_f32_16x16x32_bf16 v[14:17], v[138:141], v[190:193], v[14:17]
	v_mfma_f32_16x16x32_bf16 v[86:89], v[130:133], v[198:201], v[86:89]
	v_mfma_f32_16x16x32_bf16 v[30:33], v[138:141], v[198:201], v[30:33]
	v_mfma_f32_16x16x32_bf16 v[78:81], v[134:137], v[166:169], v[78:81]
	v_mfma_f32_16x16x32_bf16 v[22:25], v[142:145], v[166:169], v[22:25]
	v_mfma_f32_16x16x32_bf16 v[70:73], v[134:137], v[186:189], v[70:73]
	v_mfma_f32_16x16x32_bf16 v[18:21], v[142:145], v[186:189], v[18:21]
	v_mfma_f32_16x16x32_bf16 v[66:69], v[134:137], v[194:197], v[66:69]
	v_mfma_f32_16x16x32_bf16 v[14:17], v[142:145], v[194:197], v[14:17]
	v_mfma_f32_16x16x32_bf16 v[86:89], v[134:137], v[202:205], v[86:89]
	v_mfma_f32_16x16x32_bf16 v[30:33], v[142:145], v[202:205], v[30:33]
	s_setprio 0
	s_setprio 1
	v_mfma_f32_16x16x32_bf16 v[74:77], v[146:149], v[162:165], v[74:77]
	v_mfma_f32_16x16x32_bf16 v[10:13], v[154:157], v[162:165], v[10:13]
	v_mfma_f32_16x16x32_bf16 v[62:65], v[146:149], v[176:179], v[62:65]
	v_mfma_f32_16x16x32_bf16 v[6:9], v[154:157], v[176:179], v[6:9]
	v_mfma_f32_16x16x32_bf16 v[58:61], v[146:149], v[190:193], v[58:61]
	v_mfma_f32_16x16x32_bf16 v[2:5], v[154:157], v[190:193], v[2:5]
	v_mfma_f32_16x16x32_bf16 v[82:85], v[146:149], v[198:201], v[82:85]
	v_mfma_f32_16x16x32_bf16 v[26:29], v[154:157], v[198:201], v[26:29]
	v_mfma_f32_16x16x32_bf16 v[74:77], v[150:153], v[166:169], v[74:77]
	v_mfma_f32_16x16x32_bf16 v[10:13], v[158:161], v[166:169], v[10:13]
	v_mfma_f32_16x16x32_bf16 v[62:65], v[150:153], v[186:189], v[62:65]
	v_mfma_f32_16x16x32_bf16 v[6:9], v[158:161], v[186:189], v[6:9]
	v_mfma_f32_16x16x32_bf16 v[58:61], v[150:153], v[194:197], v[58:61]
	v_mfma_f32_16x16x32_bf16 v[2:5], v[158:161], v[194:197], v[2:5]
	v_mfma_f32_16x16x32_bf16 v[82:85], v[150:153], v[202:205], v[82:85]
	v_mfma_f32_16x16x32_bf16 v[26:29], v[158:161], v[202:205], v[26:29]
	s_setprio 2
	s_barrier
	s_add_i32 s19, 0, 0x18000
	s_add_i32 s24, 0, 0x1c000
	v_add_u32_e32 v142, s19, v208
	v_add_u32_e32 v158, s24, v208
	ds_read_b128 v[130:133], v142
	ds_read_b128 v[134:137], v142 offset:1024
	ds_read_b128 v[138:141], v142 offset:2048
	ds_read_b128 v[142:145], v142 offset:3072
	ds_read_b128 v[146:149], v158
	ds_read_b128 v[150:153], v158 offset:1024
	ds_read_b128 v[154:157], v158 offset:2048
	ds_read_b128 v[158:161], v158 offset:3072
	s_add_u32 s14, s14, 0x80000
	s_addc_u32 s15, s15, 0
	s_mov_b32 m0, s76
	v_lshl_add_u64 v[216:217], s[14:15], 0, v[180:181]
	ds_read_b128 v[162:165], v209 offset:32768
	ds_read_b128 v[166:169], v209 offset:33792
	ds_read_b128 v[176:179], v209 offset:34816
	ds_read_b128 v[186:189], v209 offset:35840
	ds_read_b128 v[190:193], v209 offset:36864
	ds_read_b128 v[194:197], v209 offset:37888
	ds_read_b128 v[198:201], v209 offset:38912
	ds_read_b128 v[202:205], v209 offset:39936
	global_load_lds_dwordx4 v[216:217], off
	v_lshl_add_u64 v[216:217], s[14:15], 0, v[174:175]
	s_mov_b32 m0, s77
	s_nop 0
	global_load_lds_dwordx4 v[216:217], off
	s_waitcnt vmcnt(8)
	s_waitcnt lgkmcnt(0)
	s_barrier
	s_setprio 1
	s_waitcnt lgkmcnt(0)
	v_mfma_f32_16x16x32_bf16 v[122:125], v[130:133], v[162:165], v[122:125]
	v_mfma_f32_16x16x32_bf16 v[90:93], v[138:141], v[162:165], v[90:93]
	v_mfma_f32_16x16x32_bf16 v[110:113], v[130:133], v[176:179], v[110:113]
	v_mfma_f32_16x16x32_bf16 v[46:49], v[138:141], v[176:179], v[46:49]
	v_mfma_f32_16x16x32_bf16 v[106:109], v[130:133], v[190:193], v[106:109]
	v_mfma_f32_16x16x32_bf16 v[42:45], v[138:141], v[190:193], v[42:45]
	v_mfma_f32_16x16x32_bf16 v[126:129], v[130:133], v[198:201], v[126:129]
	v_mfma_f32_16x16x32_bf16 v[54:57], v[138:141], v[198:201], v[54:57]
	v_mfma_f32_16x16x32_bf16 v[122:125], v[134:137], v[166:169], v[122:125]
	v_mfma_f32_16x16x32_bf16 v[90:93], v[142:145], v[166:169], v[90:93]
	v_mfma_f32_16x16x32_bf16 v[110:113], v[134:137], v[186:189], v[110:113]
	v_mfma_f32_16x16x32_bf16 v[46:49], v[142:145], v[186:189], v[46:49]
	v_mfma_f32_16x16x32_bf16 v[106:109], v[134:137], v[194:197], v[106:109]
	v_mfma_f32_16x16x32_bf16 v[42:45], v[142:145], v[194:197], v[42:45]
	v_mfma_f32_16x16x32_bf16 v[126:129], v[134:137], v[202:205], v[126:129]
	v_mfma_f32_16x16x32_bf16 v[54:57], v[142:145], v[202:205], v[54:57]
	s_setprio 0
	s_setprio 1
	v_mfma_f32_16x16x32_bf16 v[114:117], v[146:149], v[162:165], v[114:117]
	v_mfma_f32_16x16x32_bf16 v[94:97], v[154:157], v[162:165], v[94:97]
	v_mfma_f32_16x16x32_bf16 v[102:105], v[146:149], v[176:179], v[102:105]
	v_mfma_f32_16x16x32_bf16 v[38:41], v[154:157], v[176:179], v[38:41]
	v_mfma_f32_16x16x32_bf16 v[98:101], v[146:149], v[190:193], v[98:101]
	v_mfma_f32_16x16x32_bf16 v[34:37], v[154:157], v[190:193], v[34:37]
	v_mfma_f32_16x16x32_bf16 v[118:121], v[146:149], v[198:201], v[118:121]
	v_mfma_f32_16x16x32_bf16 v[50:53], v[154:157], v[198:201], v[50:53]
	v_mfma_f32_16x16x32_bf16 v[114:117], v[150:153], v[166:169], v[114:117]
	v_mfma_f32_16x16x32_bf16 v[94:97], v[158:161], v[166:169], v[94:97]
	v_mfma_f32_16x16x32_bf16 v[102:105], v[150:153], v[186:189], v[102:105]
	v_mfma_f32_16x16x32_bf16 v[38:41], v[158:161], v[186:189], v[38:41]
	v_mfma_f32_16x16x32_bf16 v[98:101], v[150:153], v[194:197], v[98:101]
	v_mfma_f32_16x16x32_bf16 v[34:37], v[158:161], v[194:197], v[34:37]
	v_mfma_f32_16x16x32_bf16 v[118:121], v[150:153], v[202:205], v[118:121]
	v_mfma_f32_16x16x32_bf16 v[50:53], v[158:161], v[202:205], v[50:53]
	s_setprio 2
	s_barrier
	s_add_i32 s14, s19, s41
	v_lshl_add_u64 v[170:171], v[170:171], 0, s[94:95]
	s_mov_b32 m0, s14
	ds_read_b128 v[162:165], v209 offset:49152
	ds_read_b128 v[166:169], v209 offset:50176
	ds_read_b128 v[176:179], v209 offset:51200
	ds_read_b128 v[186:189], v209 offset:52224
	ds_read_b128 v[190:193], v209 offset:53248
	ds_read_b128 v[194:197], v209 offset:54272
	ds_read_b128 v[198:201], v209 offset:55296
	ds_read_b128 v[202:205], v209 offset:56320
	global_load_lds_dwordx4 v[170:171], off
	s_add_i32 m0, s14, 0x2000
	s_add_u32 s6, s6, 0x80080
	v_lshl_add_u64 v[170:171], v[210:211], 0, s[94:95]
	s_addc_u32 s7, s7, 0
	s_add_i32 s14, s24, s41
	global_load_lds_dwordx4 v[170:171], off
	v_lshl_add_u64 v[170:171], s[6:7], 0, v[0:1]
	s_mov_b32 m0, s14
	s_nop 0
	global_load_lds_dwordx4 v[170:171], off
	v_lshl_add_u64 v[170:171], s[6:7], 0, v[172:173]
	s_add_i32 m0, s14, 0x2000
	s_nop 0
	global_load_lds_dwordx4 v[170:171], off
	v_lshl_add_u64 v[170:171], v[212:213], 0, s[94:95]
	s_mov_b32 m0, s28
	s_nop 0
	global_load_lds_dwordx4 v[170:171], off
	v_lshl_add_u64 v[170:171], v[214:215], 0, s[94:95]
	s_mov_b32 m0, s82
	s_nop 0
	global_load_lds_dwordx4 v[170:171], off
	s_waitcnt vmcnt(8)
	s_waitcnt lgkmcnt(0)
	s_barrier
	s_setprio 1
	s_waitcnt lgkmcnt(0)
	v_mfma_f32_16x16x32_bf16 v[78:81], v[130:133], v[162:165], v[78:81]
	v_mfma_f32_16x16x32_bf16 v[22:25], v[138:141], v[162:165], v[22:25]
	v_mfma_f32_16x16x32_bf16 v[70:73], v[130:133], v[176:179], v[70:73]
	v_mfma_f32_16x16x32_bf16 v[18:21], v[138:141], v[176:179], v[18:21]
	v_mfma_f32_16x16x32_bf16 v[66:69], v[130:133], v[190:193], v[66:69]
	v_mfma_f32_16x16x32_bf16 v[14:17], v[138:141], v[190:193], v[14:17]
	v_mfma_f32_16x16x32_bf16 v[86:89], v[130:133], v[198:201], v[86:89]
	v_mfma_f32_16x16x32_bf16 v[30:33], v[138:141], v[198:201], v[30:33]
	v_mfma_f32_16x16x32_bf16 v[78:81], v[134:137], v[166:169], v[78:81]
	v_mfma_f32_16x16x32_bf16 v[22:25], v[142:145], v[166:169], v[22:25]
	v_mfma_f32_16x16x32_bf16 v[70:73], v[134:137], v[186:189], v[70:73]
	v_mfma_f32_16x16x32_bf16 v[18:21], v[142:145], v[186:189], v[18:21]
	v_mfma_f32_16x16x32_bf16 v[66:69], v[134:137], v[194:197], v[66:69]
	v_mfma_f32_16x16x32_bf16 v[14:17], v[142:145], v[194:197], v[14:17]
	v_mfma_f32_16x16x32_bf16 v[86:89], v[134:137], v[202:205], v[86:89]
	v_mfma_f32_16x16x32_bf16 v[30:33], v[142:145], v[202:205], v[30:33]
	s_setprio 0
	s_setprio 1
	v_mfma_f32_16x16x32_bf16 v[74:77], v[146:149], v[162:165], v[74:77]
	v_mfma_f32_16x16x32_bf16 v[10:13], v[154:157], v[162:165], v[10:13]
	v_mfma_f32_16x16x32_bf16 v[62:65], v[146:149], v[176:179], v[62:65]
	v_mfma_f32_16x16x32_bf16 v[6:9], v[154:157], v[176:179], v[6:9]
	v_mfma_f32_16x16x32_bf16 v[58:61], v[146:149], v[190:193], v[58:61]
	v_mfma_f32_16x16x32_bf16 v[2:5], v[154:157], v[190:193], v[2:5]
	v_mfma_f32_16x16x32_bf16 v[82:85], v[146:149], v[198:201], v[82:85]
	v_mfma_f32_16x16x32_bf16 v[26:29], v[154:157], v[198:201], v[26:29]
	v_mfma_f32_16x16x32_bf16 v[74:77], v[150:153], v[166:169], v[74:77]
	v_mfma_f32_16x16x32_bf16 v[10:13], v[158:161], v[166:169], v[10:13]
	v_mfma_f32_16x16x32_bf16 v[62:65], v[150:153], v[186:189], v[62:65]
	v_mfma_f32_16x16x32_bf16 v[6:9], v[158:161], v[186:189], v[6:9]
	v_mfma_f32_16x16x32_bf16 v[58:61], v[150:153], v[194:197], v[58:61]
	v_mfma_f32_16x16x32_bf16 v[2:5], v[158:161], v[194:197], v[2:5]
	v_mfma_f32_16x16x32_bf16 v[82:85], v[150:153], v[202:205], v[82:85]
	v_mfma_f32_16x16x32_bf16 v[26:29], v[158:161], v[202:205], v[26:29]
	s_setprio 2
	s_add_i32 s18, s18, 2
	s_add_u32 s16, s16, 0x100
	s_addc_u32 s17, s17, 0
	s_add_u32 s12, s12, 0x100
	s_addc_u32 s13, s13, 0
	s_cmp_gt_u32 s18, 29
	s_barrier
	s_cbranch_scc0 .LBB0_773
	s_and_b64 vcc, exec, s[72:73]
	s_cbranch_vccz .LBB0_776
	s_barrier
